# baseline (speedup 1.0000x reference)
; DI int lbid() { int x = blockIdx.x; asm volatile("" : "+s"(x)); return x; }
; __global__ void __launch_bounds__(256, 2) trunk_fwd(Params p) {
;     ...
;     for (int t = lbid(); t < 128; t += gridDim.x) {
;       const int c = t >> 6, tt = t & 63, nt = tt & 1, mt = tt >> 1;
;       ARowCmp ar{p.qkvz + 1024 + c * 256, 3584};
;       EpiCmp1 e{p.h1 + (long)c * 4096 * 256, p.bias_part + c * 16 * 256};
;       gemm_tile(ar, 3584, p.w1t[c], 2048, 2048, mt * 128, nt * 128, e, smem);
.LBB0_675:
	s_mov_b32 s23, s43
	s_cmpk_gt_i32 s23, 0x7f
	s_cbranch_scc1 .LBB0_680
	s_load_dwordx2 s[4:5], s[56:57], 0x130
	s_load_dwordx2 s[6:7], s[56:57], 0xf8
	s_load_dwordx2 s[8:9], s[56:57], 0x148
	s_lshl_b32 s24, s23, 7
	s_lshl_b32 s25, s22, 7
	s_waitcnt lgkmcnt(0)
	s_add_u32 s10, s4, 0x2400
	s_addc_u32 s11, s5, 0
	s_lshl_b32 s26, s23, 6
	s_lshl_b32 s27, s22, 6
	s_movk_i32 s28, 0xe000
	s_movk_i32 s29, 0x1c00
	v_mov_b32_e32 v213, 0
	s_mov_b64 s[12:13], 0x800
	s_mov_b64 s[14:15], 0x1c00
	s_movk_i32 s30, 0x1000
	s_movk_i32 s31, 0x2000
	s_movk_i32 s33, 0x3000
	s_setprio 3

; DI void xcd_barrier(const XcdBarrier& b) {
;   asm volatile("s_waitcnt vmcnt(0)" ::: "memory");
;   __syncthreads();
;   if (threadIdx.x == 0) {
;     unsigned* bar = b.bar;
;     __builtin_amdgcn_s_waitcnt(0);
;     unsigned nloc = b.st[0], nx = b.st[1];
;     if (nloc == 0u) { xcd_barrier_complete(bar, b.x, nloc, nx); b.st[0] = nloc; b.st[1] = nx; }
.LBB0_680:
	s_setprio 0
	s_cmp_lt_i32 s52, 4
	s_cselect_b64 s[8:9], -1, 0
	s_cmp_gt_i32 s52, 3
	s_cselect_b64 s[0:1], -1, 0
	s_cmp_lt_i32 s54, 4
	s_cselect_b64 s[4:5], -1, 0
	s_or_b64 s[0:1], s[0:1], s[4:5]
	s_and_b64 vcc, exec, s[0:1]
	s_cbranch_vccnz .LBB0_744
	s_andn2_b64 vcc, exec, s[2:3]
	s_cbranch_vccnz .LBB0_735
	s_waitcnt vmcnt(0)
	s_barrier
	s_and_saveexec_b64 s[2:3], s[48:49]
	s_cbranch_execz .LBB0_734
	v_mov_b32_e32 v0, 0x12030
	s_waitcnt vmcnt(0) expcnt(0) lgkmcnt(0)
	ds_read_b32 v2, v0
	v_mov_b32_e32 v0, 0x12034
	ds_read_b32 v0, v0
	s_waitcnt lgkmcnt(1)
	v_cmp_ne_u32_e32 vcc, 0, v2
	s_cbranch_vccnz .LBB0_698
	s_load_dwordx2 s[6:7], s[56:57], 0x170
	s_load_dword s5, s[56:57], 0x178
	s_add_u32 s0, s44, 0x1000
	s_addc_u32 s1, s45, 0
	s_add_u32 s4, s44, 0x1100
	s_waitcnt lgkmcnt(0)
	s_mul_i32 s18, s7, s6
	s_mul_i32 s18, s18, s5
	s_addc_u32 s5, s45, 0
	s_add_u32 s6, s44, 0x1200
	s_addc_u32 s7, s45, 0
	s_add_u32 s10, s44, 0x1300
	s_addc_u32 s11, s45, 0
	s_mov_b32 s19, 1
	v_mov_b32_e32 v16, 0
	s_branch .LBB0_686
